# mout sub-unit top: vmcnt(0) before the K-tile LDS write relaxed to vmcnt(7) so the seven carried-state loads stay in flight across sync 1 and the S block; covering wait moved after sync 2
# baseline (speedup 1.0000x reference)
; #define LAS __attribute__((address_space(3)))
; __device__ __forceinline__ void mout_phase(const Params& p, LAS unsigned char* lds) {
;     ...
;         for (int i = 0; i < 4; ++i) { const int idx = t + 512 * i, r = idx >> 4, c8 = (idx & 15) * 8; *(LAS u32x4*)(T + r * 136 + c8) = kreg[i]; }
;         u32x4 creg[9];
;         { const bf16_t* cp = CP + (size_t)(chain * 32 + cc) * (272 * 128);
; #pragma unroll
;           for (int i = 0; i < 9; ++i) { const int idx = t + 512 * i; creg[i] = (u32x4){0u, 0u, 0u, 0u}; if (idx < 272 * 16) creg[i] = *(const u32x4*)(cp + (size_t)(idx >> 4) * 128 + (idx & 15) * 8); } }
.LBB0_1492:
	s_or_b64 exec, exec, s[66:67]
	s_and_b32 s66, s33, 0xffffffc0
	s_lshl_b32 s67, s82, 5
	s_bfe_u32 s70, s33, 0x50001
	s_or_b32 s66, s67, s66
	s_or_b32 s66, s66, s70
	v_mad_i64_i32 v[72:73], s[66:67], s66, v219, v[142:143]
	v_lshlrev_b32_e32 v138, 1, v146
	v_mov_b32_e32 v153, v139
	v_mov_b32_e32 v155, v139
	v_lshl_add_u64 v[36:37], v[72:73], 0, v[138:139]
	v_lshl_add_u64 v[40:41], v[72:73], 0, v[152:153]
	v_lshl_add_u64 v[44:45], v[72:73], 0, v[154:155]
	v_mov_b32_e32 v157, v139
	v_mov_b32_e32 v159, v139
	global_load_dwordx4 v[36:39], v[36:37], off
	s_nop 0
	global_load_dwordx4 v[40:43], v[40:41], off
	v_lshl_add_u64 v[46:47], v[72:73], 0, v[156:157]
	global_load_dwordx4 v[48:51], v[44:45], off
	global_load_dwordx4 v[52:55], v[46:47], off
	v_lshl_add_u64 v[44:45], v[72:73], 0, v[158:159]
	v_mov_b32_e32 v161, v139
	v_mov_b32_e32 v163, v139
	v_lshl_add_u64 v[46:47], v[72:73], 0, v[160:161]
	global_load_dwordx4 v[56:59], v[44:45], off
	global_load_dwordx4 v[60:63], v[46:47], off
	v_lshl_add_u64 v[44:45], v[72:73], 0, v[162:163]
	global_load_dwordx4 v[64:67], v[44:45], off
	v_add_u32_e32 v153, v193, v196
	v_mov_b32_e32 v44, 0
	v_mov_b32_e32 v68, 0
	v_mov_b32_e32 v69, 0
	v_mov_b32_e32 v70, 0
	v_mov_b32_e32 v71, 0
	s_waitcnt vmcnt(7)
	ds_write_b128 v153, v[0:3]
	ds_write_b128 v216, v[4:7]
	ds_write_b128 v217, v[8:11]
	ds_write_b128 v218, v[12:15]
	s_and_saveexec_b64 s[66:67], s[18:19]
	s_cbranch_execz .LBB0_1494
	v_mov_b32_e32 v165, v139
	v_lshl_add_u64 v[46:47], v[72:73], 0, v[164:165]
	global_load_dwordx4 v[68:71], v[46:47], off

; #define LAS __attribute__((address_space(3)))
; __device__ __forceinline__ unsigned cvt_pk_bf16(float lo, float hi) { unsigned r; asm volatile("v_cvt_pk_bf16_f32 %0, %1, %2" : "=v"(r) : "v"(lo), "v"(hi)); return r; }
; __device__ __forceinline__ void mout_phase(const Params& p, LAS unsigned char* lds) {
;     ...
;         __syncthreads();
;         const int j = 16 * wid + fr;
;         {
;             f32x4 S[8];
; #pragma unroll
;             for (int nb = 0; nb < 8; ++nb) S[nb] = (f32x4){0.f, 0.f, 0.f, 0.f};
; #pragma unroll
;             for (int kk = 0; kk < 4; ++kk)
; #pragma unroll
;                 for (int nb = 0; nb < 8; ++nb) { const bf16x8 kf = *(const LAS bf16x8*)(T + (nb * 16 + fr) * 136 + kk * 32 + fq * 8);
;                     S[nb] = __builtin_amdgcn_mfma_f32_16x16x32_bf16(kf, qf[kk], S[nb], 0, 0, 0); }
;             const float rb = fv[j];
; #pragma unroll
;             for (int nb = 0; nb < 8; ++nb) { const int l0 = nb * 16 + 4 * fq; const f32x4 cw = *(const LAS f32x4*)(fv + 128 + l0);
;                 float sv[4];
; #pragma unroll
;                 for (int i = 0; i < 4; ++i) { const int l = l0 + i; const bool valid = dir ? (l >= j) : (l <= j); sv[i] = valid ? S[nb][i] * __expf(rb + cw[i]) : 0.f; }
;                 u32x2 o; o.x = cvt_pk_bf16(sv[0], sv[1]); o.y = cvt_pk_bf16(sv[2], sv[3]); *(LAS u32x2*)(sb + j * 136 + l0) = o; }
.LBB0_1496:
	s_or_b64 exec, exec, s[66:67]
	s_waitcnt lgkmcnt(0)
	s_barrier
	ds_read_b128 v[72:75], v201
	ds_read_b128 v[104:107], v201 offset:64
	ds_read_b128 v[76:79], v201 offset:4352
	ds_read_b128 v[80:83], v201 offset:8704
	ds_read_b128 v[84:87], v201 offset:13056
	ds_read_b128 v[88:91], v201 offset:17408
	s_waitcnt lgkmcnt(5)
	v_mfma_f32_16x16x32_bf16 v[72:75], v[72:75], v[16:19], 0
	ds_read_b128 v[92:95], v201 offset:21760
	ds_read_b128 v[96:99], v201 offset:26112
	ds_read_b128 v[100:103], v201 offset:30464
	s_waitcnt lgkmcnt(7)
	v_mfma_f32_16x16x32_bf16 v[72:75], v[104:107], v[20:23], v[72:75]
	ds_read_b128 v[104:107], v201 offset:4416
	s_cmp_lg_u32 s82, 0
	s_cselect_b64 s[80:81], -1, 0
	s_waitcnt lgkmcnt(7)
	v_mfma_f32_16x16x32_bf16 v[76:79], v[76:79], v[16:19], 0
	s_cmp_eq_u32 s82, 0
	s_cselect_b64 vcc, -1, 0
	v_readlane_b32 s36, v254, 38
	s_waitcnt lgkmcnt(0)
	v_mfma_f32_16x16x32_bf16 v[76:79], v[104:107], v[20:23], v[76:79]
	ds_read_b128 v[104:107], v201 offset:8768
	v_readlane_b32 s37, v254, 39
	v_mfma_f32_16x16x32_bf16 v[80:83], v[80:83], v[16:19], 0
	s_waitcnt lgkmcnt(0)
	v_mfma_f32_16x16x32_bf16 v[80:83], v[104:107], v[20:23], v[80:83]
	ds_read_b128 v[104:107], v201 offset:13120
	v_mfma_f32_16x16x32_bf16 v[84:87], v[84:87], v[16:19], 0
	s_waitcnt lgkmcnt(0)
	v_mfma_f32_16x16x32_bf16 v[84:87], v[104:107], v[20:23], v[84:87]
	ds_read_b128 v[104:107], v201 offset:17472
	v_mfma_f32_16x16x32_bf16 v[88:91], v[88:91], v[16:19], 0
	s_waitcnt lgkmcnt(0)
	v_mfma_f32_16x16x32_bf16 v[88:91], v[104:107], v[20:23], v[88:91]
	ds_read_b128 v[104:107], v201 offset:21824
	v_mfma_f32_16x16x32_bf16 v[92:95], v[92:95], v[16:19], 0
	s_waitcnt lgkmcnt(0)
	v_mfma_f32_16x16x32_bf16 v[92:95], v[104:107], v[20:23], v[92:95]
	ds_read_b128 v[104:107], v201 offset:26176
	v_mfma_f32_16x16x32_bf16 v[96:99], v[96:99], v[16:19], 0
	s_waitcnt lgkmcnt(0)
	v_mfma_f32_16x16x32_bf16 v[96:99], v[104:107], v[20:23], v[96:99]
	ds_read_b128 v[104:107], v201 offset:30528
	v_mfma_f32_16x16x32_bf16 v[100:103], v[100:103], v[16:19], 0
	s_waitcnt lgkmcnt(0)
	v_mfma_f32_16x16x32_bf16 v[100:103], v[104:107], v[20:23], v[100:103]
	ds_read_b128 v[228:231], v201 offset:128
	ds_read_b128 v[232:235], v201 offset:4480
	ds_read_b128 v[236:239], v201 offset:8832
	s_waitcnt lgkmcnt(2)
	v_mfma_f32_16x16x32_bf16 v[72:75], v[228:231], v[24:27], v[72:75]
	ds_read_b128 v[104:107], v201 offset:13184
	s_waitcnt lgkmcnt(2)
	v_mfma_f32_16x16x32_bf16 v[76:79], v[232:235], v[24:27], v[76:79]
	s_waitcnt lgkmcnt(1)
	v_mfma_f32_16x16x32_bf16 v[80:83], v[236:239], v[24:27], v[80:83]
	s_waitcnt lgkmcnt(0)
	v_mfma_f32_16x16x32_bf16 v[84:87], v[104:107], v[24:27], v[84:87]
	ds_read_b128 v[104:107], v201 offset:17536
	s_waitcnt lgkmcnt(0)
	v_mfma_f32_16x16x32_bf16 v[104:107], v[104:107], v[24:27], v[88:91]
	s_nop 2
	ds_read_b128 v[228:231], v201 offset:21888
	ds_read_b128 v[232:235], v201 offset:26240
	ds_read_b128 v[236:239], v201 offset:30592
	s_waitcnt lgkmcnt(2)
	v_mfma_f32_16x16x32_bf16 v[108:111], v[228:231], v[24:27], v[92:95]
	ds_read_b128 v[88:91], v201 offset:192
	s_waitcnt lgkmcnt(2)
	v_mfma_f32_16x16x32_bf16 v[112:115], v[232:235], v[24:27], v[96:99]
	s_waitcnt lgkmcnt(1)
	v_mfma_f32_16x16x32_bf16 v[116:119], v[236:239], v[24:27], v[100:103]
	s_waitcnt lgkmcnt(0)
	v_mfma_f32_16x16x32_bf16 v[100:103], v[88:91], v[28:31], v[72:75]
	s_nop 2
	ds_read_b128 v[228:231], v201 offset:4544
	ds_read_b128 v[232:235], v201 offset:8896
	ds_read_b128 v[236:239], v201 offset:13248
	s_waitcnt lgkmcnt(2)
	v_mfma_f32_16x16x32_bf16 v[96:99], v[228:231], v[28:31], v[76:79]
	ds_read_b128 v[72:75], v201 offset:17600
	s_waitcnt lgkmcnt(2)
	v_mfma_f32_16x16x32_bf16 v[92:95], v[232:235], v[28:31], v[80:83]
	s_waitcnt lgkmcnt(1)
	v_mfma_f32_16x16x32_bf16 v[88:91], v[236:239], v[28:31], v[84:87]
	s_waitcnt lgkmcnt(0)
	v_mfma_f32_16x16x32_bf16 v[84:87], v[72:75], v[28:31], v[104:107]
	ds_read_b128 v[72:75], v201 offset:21952
	s_nop 1
	ds_read_b32 v104, v195
	v_cndmask_b32_e64 v105, 0, 1, s[94:95]
	s_waitcnt lgkmcnt(1)
	v_mfma_f32_16x16x32_bf16 v[80:83], v[72:75], v[28:31], v[108:111]
	ds_read_b128 v[72:75], v201 offset:26304
	s_nop 1
	ds_read_b128 v[106:109], v202
	v_cndmask_b32_e64 v110, 0, 1, s[92:93]
	v_cndmask_b32_e32 v105, v110, v105, vcc
	v_and_b32_e32 v105, 1, v105
	v_cmp_eq_u32_e64 s[66:67], 1, v105
	s_waitcnt lgkmcnt(0)
	v_add_f32_e32 v105, v104, v106
	v_mul_f32_e32 v105, 0x3fb8aa3b, v105
	v_exp_f32_e32 v105, v105
	v_cndmask_b32_e64 v106, 0, 1, s[96:97]
	v_mfma_f32_16x16x32_bf16 v[76:79], v[72:75], v[28:31], v[112:115]
	ds_read_b128 v[72:75], v201 offset:30656
	v_mul_f32_e32 v100, v100, v105
	v_cndmask_b32_e64 v105, 0, 1, s[6:7]
	v_cndmask_b32_e32 v105, v106, v105, vcc
	v_and_b32_e32 v105, 1, v105
	v_cndmask_b32_e64 v100, 0, v100, s[66:67]
	v_cmp_eq_u32_e64 s[66:67], 1, v105
	v_add_f32_e32 v105, v104, v107
	v_mul_f32_e32 v105, 0x3fb8aa3b, v105
	v_exp_f32_e32 v105, v105
	v_cndmask_b32_e64 v106, 0, 1, s[8:9]
	s_waitcnt lgkmcnt(0)
	v_mfma_f32_16x16x32_bf16 v[72:75], v[72:75], v[28:31], v[116:119]
	v_mul_f32_e32 v101, v101, v105
	v_cndmask_b32_e64 v105, 0, 1, s[10:11]
	v_cndmask_b32_e32 v105, v106, v105, vcc
	v_and_b32_e32 v105, 1, v105
	v_cndmask_b32_e64 v101, 0, v101, s[66:67]
	v_cmp_eq_u32_e64 s[66:67], 1, v105
	v_add_f32_e32 v105, v104, v108
	v_mul_f32_e32 v105, 0x3fb8aa3b, v105
	v_exp_f32_e32 v105, v105
	v_cndmask_b32_e64 v106, 0, 1, s[12:13]
	v_cvt_pk_bf16_f32 v100, v100, v101
	v_mul_f32_e32 v102, v102, v105
	v_cndmask_b32_e64 v105, 0, 1, s[14:15]
	v_cndmask_b32_e32 v105, v106, v105, vcc
	v_and_b32_e32 v105, 1, v105
	v_cndmask_b32_e64 v102, 0, v102, s[66:67]
	v_cmp_eq_u32_e64 s[66:67], 1, v105
	v_add_f32_e32 v105, v104, v109
	v_mul_f32_e32 v105, 0x3fb8aa3b, v105
	v_exp_f32_e32 v105, v105
	v_cndmask_b32_e64 v106, 0, 1, s[16:17]
	v_mul_f32_e32 v103, v103, v105
	v_cndmask_b32_e64 v103, 0, v103, s[66:67]
	v_cvt_pk_bf16_f32 v101, v102, v103
	ds_write_b64 v203, v[100:101]
	ds_read_b128 v[100:103], v204
	v_cndmask_b32_e64 v105, 0, 1, s[22:23]
	v_cndmask_b32_e32 v105, v106, v105, vcc
	v_and_b32_e32 v105, 1, v105
	v_cmp_eq_u32_e64 s[66:67], 1, v105
	s_waitcnt lgkmcnt(0)
; #define LAS __attribute__((address_space(3)))
; __device__ __forceinline__ unsigned cvt_pk_bf16(float lo, float hi) { unsigned r; asm volatile("v_cvt_pk_bf16_f32 %0, %1, %2" : "=v"(r) : "v"(lo), "v"(hi)); return r; }
; __device__ __forceinline__ void mout_phase(const Params& p, LAS unsigned char* lds) {
;     ...
;             const float rb = fv[j];
; #pragma unroll
;             for (int nb = 0; nb < 8; ++nb) { const int l0 = nb * 16 + 4 * fq; const f32x4 cw = *(const LAS f32x4*)(fv + 128 + l0);
;                 float sv[4];
; #pragma unroll
;                 for (int i = 0; i < 4; ++i) { const int l = l0 + i; const bool valid = dir ? (l >= j) : (l <= j); sv[i] = valid ? S[nb][i] * __expf(rb + cw[i]) : 0.f; }
;                 u32x2 o; o.x = cvt_pk_bf16(sv[0], sv[1]); o.y = cvt_pk_bf16(sv[2], sv[3]); *(LAS u32x2*)(sb + j * 136 + l0) = o; }
	v_add_f32_e32 v100, v104, v100
	v_mul_f32_e32 v100, 0x3fb8aa3b, v100
	v_exp_f32_e32 v100, v100
	v_cndmask_b32_e64 v105, 0, 1, s[24:25]
	v_mul_f32_e32 v96, v96, v100
	v_cndmask_b32_e64 v100, 0, 1, s[26:27]
	v_cndmask_b32_e32 v100, v105, v100, vcc
	v_and_b32_e32 v100, 1, v100
	v_cndmask_b32_e64 v96, 0, v96, s[66:67]
	v_cmp_eq_u32_e64 s[66:67], 1, v100
	v_add_f32_e32 v100, v104, v101
	v_mul_f32_e32 v100, 0x3fb8aa3b, v100
	v_exp_f32_e32 v100, v100
	v_cndmask_b32_e64 v101, 0, 1, s[28:29]
	v_mul_f32_e32 v97, v97, v100
	v_cndmask_b32_e64 v100, 0, 1, s[30:31]
	v_cndmask_b32_e32 v100, v101, v100, vcc
	v_and_b32_e32 v100, 1, v100
	v_cndmask_b32_e64 v97, 0, v97, s[66:67]
	v_cmp_eq_u32_e64 s[66:67], 1, v100
	v_add_f32_e32 v100, v104, v102
	v_mul_f32_e32 v100, 0x3fb8aa3b, v100
	v_exp_f32_e32 v100, v100
	v_cndmask_b32_e64 v101, 0, 1, s[34:35]
	v_cvt_pk_bf16_f32 v96, v96, v97
	v_mul_f32_e32 v98, v98, v100
	v_cndmask_b32_e64 v100, 0, 1, s[36:37]
	v_cndmask_b32_e32 v100, v101, v100, vcc
	v_and_b32_e32 v100, 1, v100
	v_cndmask_b32_e64 v98, 0, v98, s[66:67]
	v_cmp_eq_u32_e64 s[66:67], 1, v100
	v_add_f32_e32 v100, v104, v103
	v_mul_f32_e32 v100, 0x3fb8aa3b, v100
	v_exp_f32_e32 v100, v100
	v_readlane_b32 s36, v254, 42
	v_readlane_b32 s37, v254, 43
	v_mul_f32_e32 v99, v99, v100
	v_cndmask_b32_e64 v99, 0, v99, s[66:67]
	v_cvt_pk_bf16_f32 v97, v98, v99
	ds_write_b64 v203, v[96:97] offset:32
	ds_read_b128 v[96:99], v205
	v_cndmask_b32_e64 v100, 0, 1, s[36:37]
	v_readlane_b32 s36, v254, 40
	v_readlane_b32 s37, v254, 41
	s_waitcnt lgkmcnt(0)
	v_add_f32_e32 v96, v104, v96
	v_mul_f32_e32 v96, 0x3fb8aa3b, v96
	v_exp_f32_e32 v96, v96
	v_cndmask_b32_e64 v101, 0, 1, s[36:37]
	v_readlane_b32 s36, v254, 46
	v_readlane_b32 s37, v254, 47
	v_cndmask_b32_e32 v100, v101, v100, vcc
	v_mul_f32_e32 v92, v92, v96
	v_cndmask_b32_e64 v96, 0, 1, s[36:37]
	v_readlane_b32 s36, v254, 44
	v_and_b32_e32 v100, 1, v100
	v_readlane_b32 s37, v254, 45
	v_cmp_eq_u32_e64 s[66:67], 1, v100
	s_nop 0
	v_cndmask_b32_e64 v100, 0, 1, s[36:37]
	v_cndmask_b32_e32 v96, v100, v96, vcc
	v_and_b32_e32 v96, 1, v96
	v_cndmask_b32_e64 v92, 0, v92, s[66:67]
	v_cmp_eq_u32_e64 s[66:67], 1, v96
	v_add_f32_e32 v96, v104, v97
	v_mul_f32_e32 v96, 0x3fb8aa3b, v96
	v_exp_f32_e32 v96, v96
	v_readlane_b32 s36, v254, 50
	v_readlane_b32 s37, v254, 51
	v_mul_f32_e32 v93, v93, v96
	s_nop 0
	v_cndmask_b32_e64 v96, 0, 1, s[36:37]
	v_readlane_b32 s36, v254, 48
	v_readlane_b32 s37, v254, 49
	v_cndmask_b32_e64 v93, 0, v93, s[66:67]
	v_cvt_pk_bf16_f32 v92, v92, v93
	s_nop 0
	v_cndmask_b32_e64 v97, 0, 1, s[36:37]
	v_cndmask_b32_e32 v96, v97, v96, vcc
	v_and_b32_e32 v96, 1, v96
	v_cmp_eq_u32_e64 s[66:67], 1, v96
	v_add_f32_e32 v96, v104, v98
	v_mul_f32_e32 v96, 0x3fb8aa3b, v96
	v_exp_f32_e32 v96, v96
	v_readlane_b32 s36, v254, 54
	v_readlane_b32 s37, v254, 55
	v_mul_f32_e32 v94, v94, v96
	s_nop 0
	v_cndmask_b32_e64 v96, 0, 1, s[36:37]
	v_readlane_b32 s36, v254, 52
	v_readlane_b32 s37, v254, 53
	v_cndmask_b32_e64 v94, 0, v94, s[66:67]
	s_nop 0
	v_cndmask_b32_e64 v97, 0, 1, s[36:37]
	v_cndmask_b32_e32 v96, v97, v96, vcc
	v_and_b32_e32 v96, 1, v96
	v_cmp_eq_u32_e64 s[66:67], 1, v96
	v_add_f32_e32 v96, v104, v99
	v_mul_f32_e32 v96, 0x3fb8aa3b, v96
	v_exp_f32_e32 v96, v96
	v_readlane_b32 s36, v254, 56
	v_readlane_b32 s37, v254, 57
	v_mul_f32_e32 v95, v95, v96
	v_cndmask_b32_e64 v95, 0, v95, s[66:67]
	v_cvt_pk_bf16_f32 v93, v94, v95
	ds_write_b64 v203, v[92:93] offset:64
	ds_read_b128 v[92:95], v206
	v_cndmask_b32_e64 v96, 0, 1, s[36:37]
	v_readlane_b32 s36, v254, 2
	v_readlane_b32 s37, v254, 3
	s_waitcnt lgkmcnt(0)
	v_add_f32_e32 v92, v104, v92
	v_mul_f32_e32 v92, 0x3fb8aa3b, v92
	v_exp_f32_e32 v92, v92
	v_cndmask_b32_e64 v97, 0, 1, s[36:37]
	v_readlane_b32 s36, v254, 60
	v_readlane_b32 s37, v254, 61
	v_cndmask_b32_e32 v96, v97, v96, vcc
	v_mul_f32_e32 v88, v88, v92
	v_cndmask_b32_e64 v92, 0, 1, s[36:37]
	v_readlane_b32 s36, v254, 58
	v_and_b32_e32 v96, 1, v96
	v_readlane_b32 s37, v254, 59
	v_cmp_eq_u32_e64 s[66:67], 1, v96
	s_nop 0
	v_cndmask_b32_e64 v96, 0, 1, s[36:37]
	v_cndmask_b32_e32 v92, v96, v92, vcc
	v_and_b32_e32 v92, 1, v92
	v_cndmask_b32_e64 v88, 0, v88, s[66:67]
	v_cmp_eq_u32_e64 s[66:67], 1, v92
	v_add_f32_e32 v92, v104, v93
	v_mul_f32_e32 v92, 0x3fb8aa3b, v92
	v_exp_f32_e32 v92, v92
	v_readlane_b32 s36, v255, 0
	v_readlane_b32 s37, v255, 1
	v_mul_f32_e32 v89, v89, v92
	s_nop 0
	v_cndmask_b32_e64 v92, 0, 1, s[36:37]
	v_readlane_b32 s36, v254, 62
	v_readlane_b32 s37, v254, 63
	v_cndmask_b32_e64 v89, 0, v89, s[66:67]
	v_cvt_pk_bf16_f32 v88, v88, v89
	s_nop 0
	v_cndmask_b32_e64 v93, 0, 1, s[36:37]
	v_cndmask_b32_e32 v92, v93, v92, vcc
	v_and_b32_e32 v92, 1, v92
	v_cmp_eq_u32_e64 s[66:67], 1, v92
	v_add_f32_e32 v92, v104, v94
	v_mul_f32_e32 v92, 0x3fb8aa3b, v92
	v_exp_f32_e32 v92, v92
	v_readlane_b32 s36, v255, 4
	v_readlane_b32 s37, v255, 5
	v_mul_f32_e32 v90, v90, v92
	s_nop 0
	v_cndmask_b32_e64 v92, 0, 1, s[36:37]
	v_readlane_b32 s36, v255, 2
	v_readlane_b32 s37, v255, 3
	v_cndmask_b32_e64 v90, 0, v90, s[66:67]
	s_nop 0
	v_cndmask_b32_e64 v93, 0, 1, s[36:37]
	v_cndmask_b32_e32 v92, v93, v92, vcc
	v_and_b32_e32 v92, 1, v92
	v_cmp_eq_u32_e64 s[66:67], 1, v92
	v_add_f32_e32 v92, v104, v95
	v_mul_f32_e32 v92, 0x3fb8aa3b, v92
	v_exp_f32_e32 v92, v92
	v_readlane_b32 s36, v255, 8
	v_readlane_b32 s37, v255, 9
	v_mul_f32_e32 v91, v91, v92
	v_cndmask_b32_e64 v91, 0, v91, s[66:67]
	v_cvt_pk_bf16_f32 v89, v90, v91
	ds_write_b64 v203, v[88:89] offset:96
	ds_read_b128 v[88:91], v207
	v_cndmask_b32_e64 v92, 0, 1, s[36:37]
	v_readlane_b32 s36, v255, 6
	v_readlane_b32 s37, v255, 7
	s_waitcnt lgkmcnt(0)
; #define LAS __attribute__((address_space(3)))
; __device__ __forceinline__ unsigned cvt_pk_bf16(float lo, float hi) { unsigned r; asm volatile("v_cvt_pk_bf16_f32 %0, %1, %2" : "=v"(r) : "v"(lo), "v"(hi)); return r; }
; __device__ __forceinline__ void mout_phase(const Params& p, LAS unsigned char* lds) {
;     ...
;             const float rb = fv[j];
; #pragma unroll
;             for (int nb = 0; nb < 8; ++nb) { const int l0 = nb * 16 + 4 * fq; const f32x4 cw = *(const LAS f32x4*)(fv + 128 + l0);
;                 float sv[4];
; #pragma unroll
;                 for (int i = 0; i < 4; ++i) { const int l = l0 + i; const bool valid = dir ? (l >= j) : (l <= j); sv[i] = valid ? S[nb][i] * __expf(rb + cw[i]) : 0.f; }
;                 u32x2 o; o.x = cvt_pk_bf16(sv[0], sv[1]); o.y = cvt_pk_bf16(sv[2], sv[3]); *(LAS u32x2*)(sb + j * 136 + l0) = o; }
;         }
;         __syncthreads();
	v_add_f32_e32 v88, v104, v88
	v_mul_f32_e32 v88, 0x3fb8aa3b, v88
	v_exp_f32_e32 v88, v88
	v_cndmask_b32_e64 v93, 0, 1, s[36:37]
	v_readlane_b32 s36, v255, 12
	v_readlane_b32 s37, v255, 13
	v_cndmask_b32_e32 v92, v93, v92, vcc
	v_mul_f32_e32 v84, v84, v88
	v_cndmask_b32_e64 v88, 0, 1, s[36:37]
	v_readlane_b32 s36, v255, 10
	v_and_b32_e32 v92, 1, v92
	v_readlane_b32 s37, v255, 11
	v_cmp_eq_u32_e64 s[66:67], 1, v92
	s_nop 0
	v_cndmask_b32_e64 v92, 0, 1, s[36:37]
	v_cndmask_b32_e32 v88, v92, v88, vcc
	v_and_b32_e32 v88, 1, v88
	v_cndmask_b32_e64 v84, 0, v84, s[66:67]
	v_cmp_eq_u32_e64 s[66:67], 1, v88
	v_add_f32_e32 v88, v104, v89
	v_mul_f32_e32 v88, 0x3fb8aa3b, v88
	v_exp_f32_e32 v88, v88
	v_readlane_b32 s36, v255, 16
	v_readlane_b32 s37, v255, 17
	v_mul_f32_e32 v85, v85, v88
	s_nop 0
	v_cndmask_b32_e64 v88, 0, 1, s[36:37]
	v_readlane_b32 s36, v255, 14
	v_readlane_b32 s37, v255, 15
	v_cndmask_b32_e64 v85, 0, v85, s[66:67]
	v_cvt_pk_bf16_f32 v84, v84, v85
	s_nop 0
	v_cndmask_b32_e64 v89, 0, 1, s[36:37]
	v_cndmask_b32_e32 v88, v89, v88, vcc
	v_and_b32_e32 v88, 1, v88
	v_cmp_eq_u32_e64 s[66:67], 1, v88
	v_add_f32_e32 v88, v104, v90
	v_mul_f32_e32 v88, 0x3fb8aa3b, v88
	v_exp_f32_e32 v88, v88
	v_readlane_b32 s36, v255, 20
	v_readlane_b32 s37, v255, 21
	v_mul_f32_e32 v86, v86, v88
	s_nop 0
	v_cndmask_b32_e64 v88, 0, 1, s[36:37]
	v_readlane_b32 s36, v255, 18
	v_readlane_b32 s37, v255, 19
	v_cndmask_b32_e64 v86, 0, v86, s[66:67]
	s_nop 0
	v_cndmask_b32_e64 v89, 0, 1, s[36:37]
	v_cndmask_b32_e32 v88, v89, v88, vcc
	v_and_b32_e32 v88, 1, v88
	v_cmp_eq_u32_e64 s[66:67], 1, v88
	v_add_f32_e32 v88, v104, v91
	v_mul_f32_e32 v88, 0x3fb8aa3b, v88
	v_exp_f32_e32 v88, v88
	v_readlane_b32 s36, v255, 24
	v_readlane_b32 s37, v255, 25
	v_mul_f32_e32 v87, v87, v88
	v_cndmask_b32_e64 v87, 0, v87, s[66:67]
	v_cvt_pk_bf16_f32 v85, v86, v87
	ds_write_b64 v203, v[84:85] offset:128
	ds_read_b128 v[84:87], v208
	v_cndmask_b32_e64 v88, 0, 1, s[36:37]
	v_readlane_b32 s36, v255, 22
	v_readlane_b32 s37, v255, 23
	s_waitcnt lgkmcnt(0)
	v_add_f32_e32 v84, v104, v84
	v_mul_f32_e32 v84, 0x3fb8aa3b, v84
	v_exp_f32_e32 v84, v84
	v_cndmask_b32_e64 v89, 0, 1, s[36:37]
	v_readlane_b32 s36, v255, 28
	v_readlane_b32 s37, v255, 29
	v_cndmask_b32_e32 v88, v89, v88, vcc
	v_mul_f32_e32 v80, v80, v84
	v_cndmask_b32_e64 v84, 0, 1, s[36:37]
	v_readlane_b32 s36, v255, 26
	v_and_b32_e32 v88, 1, v88
	v_readlane_b32 s37, v255, 27
	v_cmp_eq_u32_e64 s[66:67], 1, v88
	s_nop 0
	v_cndmask_b32_e64 v88, 0, 1, s[36:37]
	v_cndmask_b32_e32 v84, v88, v84, vcc
	v_and_b32_e32 v84, 1, v84
	v_cndmask_b32_e64 v80, 0, v80, s[66:67]
	v_cmp_eq_u32_e64 s[66:67], 1, v84
	v_add_f32_e32 v84, v104, v85
	v_mul_f32_e32 v84, 0x3fb8aa3b, v84
	v_exp_f32_e32 v84, v84
	v_readlane_b32 s36, v255, 54
	v_readlane_b32 s37, v255, 55
	v_mul_f32_e32 v81, v81, v84
	s_nop 0
	v_cndmask_b32_e64 v84, 0, 1, s[36:37]
	v_readlane_b32 s36, v255, 52
	v_readlane_b32 s37, v255, 53
	v_cndmask_b32_e64 v81, 0, v81, s[66:67]
	v_cvt_pk_bf16_f32 v80, v80, v81
	s_nop 0
	v_cndmask_b32_e64 v85, 0, 1, s[36:37]
	v_cndmask_b32_e32 v84, v85, v84, vcc
	v_and_b32_e32 v84, 1, v84
	v_cmp_eq_u32_e64 s[66:67], 1, v84
	v_add_f32_e32 v84, v104, v86
	v_mul_f32_e32 v84, 0x3fb8aa3b, v84
	v_exp_f32_e32 v84, v84
	v_readlane_b32 s36, v255, 58
	v_readlane_b32 s37, v255, 59
	v_mul_f32_e32 v82, v82, v84
	s_nop 0
	v_cndmask_b32_e64 v84, 0, 1, s[36:37]
	v_readlane_b32 s36, v255, 56
	v_readlane_b32 s37, v255, 57
	v_cndmask_b32_e64 v82, 0, v82, s[66:67]
	s_nop 0
	v_cndmask_b32_e64 v85, 0, 1, s[36:37]
	v_cndmask_b32_e32 v84, v85, v84, vcc
	v_and_b32_e32 v84, 1, v84
	v_cmp_eq_u32_e64 s[66:67], 1, v84
	v_add_f32_e32 v84, v104, v87
	v_mul_f32_e32 v84, 0x3fb8aa3b, v84
	v_exp_f32_e32 v84, v84
	v_readlane_b32 s36, v255, 62
	v_readlane_b32 s37, v255, 63
	v_mul_f32_e32 v83, v83, v84
	v_cndmask_b32_e64 v83, 0, v83, s[66:67]
	v_cvt_pk_bf16_f32 v81, v82, v83
	ds_write_b64 v203, v[80:81] offset:160
	ds_read_b128 v[80:83], v209
	v_cndmask_b32_e64 v84, 0, 1, s[36:37]
	v_readlane_b32 s36, v255, 60
	v_readlane_b32 s37, v255, 61
	s_waitcnt lgkmcnt(0)
	v_add_f32_e32 v80, v104, v80
	v_mul_f32_e32 v80, 0x3fb8aa3b, v80
	v_exp_f32_e32 v80, v80
	v_cndmask_b32_e64 v85, 0, 1, s[36:37]
	v_cndmask_b32_e32 v84, v85, v84, vcc
	v_and_b32_e32 v84, 1, v84
	v_cmp_eq_u32_e64 s[66:67], 1, v84
	v_mul_f32_e32 v76, v76, v80
	v_cndmask_b32_e64 v80, 0, 1, s[40:41]
	v_cndmask_b32_e64 v84, 0, 1, s[38:39]
	v_cndmask_b32_e32 v80, v84, v80, vcc
	v_and_b32_e32 v80, 1, v80
	v_cndmask_b32_e64 v76, 0, v76, s[66:67]
	v_cmp_eq_u32_e64 s[66:67], 1, v80
	v_add_f32_e32 v80, v104, v81
	v_mul_f32_e32 v80, 0x3fb8aa3b, v80
	v_exp_f32_e32 v80, v80
	v_cndmask_b32_e64 v81, 0, 1, s[42:43]
	v_mul_f32_e32 v77, v77, v80
	v_cndmask_b32_e64 v80, 0, 1, s[44:45]
	v_cndmask_b32_e32 v80, v81, v80, vcc
	v_and_b32_e32 v80, 1, v80
	v_cndmask_b32_e64 v77, 0, v77, s[66:67]
	v_cmp_eq_u32_e64 s[66:67], 1, v80
	v_add_f32_e32 v80, v104, v82
	v_mul_f32_e32 v80, 0x3fb8aa3b, v80
	v_exp_f32_e32 v80, v80
	v_cndmask_b32_e64 v81, 0, 1, s[46:47]
	v_cvt_pk_bf16_f32 v76, v76, v77
	v_mul_f32_e32 v78, v78, v80
	v_cndmask_b32_e64 v80, 0, 1, s[48:49]
	v_cndmask_b32_e32 v80, v81, v80, vcc
	v_and_b32_e32 v80, 1, v80
	v_cndmask_b32_e64 v78, 0, v78, s[66:67]
	v_cmp_eq_u32_e64 s[66:67], 1, v80
	v_add_f32_e32 v80, v104, v83
	v_mul_f32_e32 v80, 0x3fb8aa3b, v80
	v_exp_f32_e32 v80, v80
	v_cndmask_b32_e64 v81, 0, 1, s[50:51]
	v_mul_f32_e32 v79, v79, v80
	v_cndmask_b32_e64 v79, 0, v79, s[66:67]
	v_cvt_pk_bf16_f32 v77, v78, v79
	ds_write_b64 v203, v[76:77] offset:192
	ds_read_b128 v[76:79], v210
	v_cndmask_b32_e64 v80, 0, 1, s[52:53]
	v_cndmask_b32_e32 v80, v81, v80, vcc
	v_and_b32_e32 v80, 1, v80
	v_cmp_eq_u32_e64 s[66:67], 1, v80
	s_waitcnt lgkmcnt(0)
	v_add_f32_e32 v76, v104, v76
	v_mul_f32_e32 v76, 0x3fb8aa3b, v76
	v_exp_f32_e32 v76, v76
	v_cndmask_b32_e64 v80, 0, 1, s[54:55]
	v_mul_f32_e32 v72, v72, v76
	v_cndmask_b32_e64 v76, 0, 1, s[56:57]
	v_cndmask_b32_e32 v76, v80, v76, vcc
	v_and_b32_e32 v76, 1, v76
	v_cndmask_b32_e64 v72, 0, v72, s[66:67]
	v_cmp_eq_u32_e64 s[66:67], 1, v76
	v_add_f32_e32 v76, v104, v77
	v_mul_f32_e32 v76, 0x3fb8aa3b, v76
	v_exp_f32_e32 v76, v76
	v_cndmask_b32_e64 v77, 0, 1, s[58:59]
	v_mul_f32_e32 v73, v73, v76
	v_cndmask_b32_e64 v76, 0, 1, s[60:61]
	v_cndmask_b32_e32 v76, v77, v76, vcc
	v_and_b32_e32 v76, 1, v76
	v_cndmask_b32_e64 v73, 0, v73, s[66:67]
	v_cmp_eq_u32_e64 s[66:67], 1, v76
	v_add_f32_e32 v76, v104, v78
	v_mul_f32_e32 v76, 0x3fb8aa3b, v76
	v_exp_f32_e32 v76, v76
	v_cndmask_b32_e64 v77, 0, 1, s[62:63]
	v_cvt_pk_bf16_f32 v72, v72, v73
	v_mul_f32_e32 v74, v74, v76
	v_cndmask_b32_e64 v76, 0, 1, s[64:65]
	v_cndmask_b32_e32 v76, v77, v76, vcc
	v_and_b32_e32 v76, 1, v76
	v_cmp_eq_u32_e32 vcc, 1, v76
	v_add_f32_e32 v76, v104, v79
	v_mul_f32_e32 v76, 0x3fb8aa3b, v76
	v_exp_f32_e32 v76, v76
	v_cndmask_b32_e64 v74, 0, v74, s[66:67]
	v_mul_f32_e32 v75, v75, v76
	v_cndmask_b32_e32 v75, 0, v75, vcc
	v_cvt_pk_bf16_f32 v73, v74, v75
	ds_write_b64 v203, v[72:73] offset:224
	s_waitcnt lgkmcnt(0)
	s_barrier
; #define LAS __attribute__((address_space(3)))
; __device__ __forceinline__ void mout_phase(const Params& p, LAS unsigned char* lds) {
;     ...
;         __syncthreads();
; #pragma unroll
;         for (int i = 0; i < 9; ++i) { const int idx = t + 512 * i; if (idx < 272 * 16) *(LAS u32x4*)(T + (idx >> 4) * 136 + (idx & 15) * 8) = creg[i]; }
	s_waitcnt vmcnt(0)
	ds_write_b128 v153, v[36:39]
	ds_write_b128 v216, v[40:43]
	ds_write_b128 v217, v[48:51]
	ds_write_b128 v218, v[52:55]
	ds_write_b128 v220, v[56:59]
	ds_write_b128 v221, v[60:63]
	ds_write_b128 v222, v[64:67]
	s_and_saveexec_b64 s[66:67], s[18:19]
	s_cbranch_execz .LBB0_1498
	s_waitcnt vmcnt(0)
	ds_write_b128 v223, v[68:71]
